# mLSTM: L2 warm-up loads run two chunks ahead of the LDS-DMA staging
# speedup vs baseline: 1.0153x; 1.0094x over previous
; __device__ __forceinline__ void mlstm_item(const Args& a, LAS unsigned char* L, bool sample, int b, int hh, int sl, bool dry = false) {
;     ...
;         if (c + 1 < nchunks) PREFETCH(c + 1);
.LBB0_665:
	s_or_b64 exec, exec, s[72:73]
	v_lshl_add_u64 v[8:9], v[74:75], 0, s[70:71]
	v_add_co_u32_e32 v0, vcc, 0xe2000, v8
	s_nop 1
	v_addc_co_u32_e32 v1, vcc, 0, v9, vcc
	v_add_co_u32_e32 v8, vcc, 0x11a000, v8
	global_load_dwordx4 v[4:7], v[0:1], off
	s_nop 0
	global_load_dwordx4 v[0:3], v[0:1], off offset:2048
	v_addc_co_u32_e32 v9, vcc, 0, v9, vcc
	global_load_dwordx4 v[12:15], v[8:9], off
	s_nop 0
	global_load_dwordx4 v[8:11], v[8:9], off offset:2048
	s_and_saveexec_b64 s[72:73], s[0:1]
	s_cbranch_execz .LBB0_667
	v_lshl_add_u64 v[56:57], v[72:73], 0, s[70:71]
	v_add_co_u32_e32 v58, vcc, 0x73000, v56
	s_nop 1
	v_addc_co_u32_e32 v59, vcc, 0, v57, vcc
	v_add_co_u32_e32 v56, vcc, 0x76000, v56
	s_nop 1
	v_addc_co_u32_e32 v57, vcc, 0, v57, vcc
	global_load_dwordx2 v[62:63], v[58:59], off
	global_load_dwordx2 v[64:65], v[56:57], off offset:2048
